# FFN1 SwiGLU epilogue with packed f32 VALU ops (same per-element f32 operations, half the issue slots)
# speedup vs baseline: 1.0153x; 1.0033x over previous
; __device__ __forceinline__ unsigned pk_bf16(float lo, float hi) { unsigned r; asm volatile("v_cvt_pk_bf16_f32 %0, %1, %2" : "=v"(r) : "v"(lo), "v"(hi)); return r; }
;     __device__ __forceinline__ void operator()(const f32x4 (&acc)[2][2][4][2], const Unit& u, int wr, int wc, int fr, int fq) const {
;         const int row0 = wr * 64 + fr, col0 = wc * 32 + 8 * fq;
; #pragma unroll
;         for (int ai = 0; ai < 2; ++ai) if (ai == 0 || u.half == 0)
; #pragma unroll
;             for (int m = 0; m < 4; ++m) { bf16_t* rowp = (bf16_t*)u.o + (size_t)(row0 + ai * HALF + m * 16) * u.ldo + col0; float r[8];
; #pragma unroll
;                 for (int bj = 0; bj < 2; ++bj) { const f32x4 a = acc[ai][bj][m][0], b = acc[ai][bj][m][1];
; #pragma unroll
;                     for (int e = 0; e < 4; ++e) r[bj * 4 + e] = a[e] * b[e] * __builtin_amdgcn_rcpf(1.f + __expf(-a[e])); }
;                 u32x4 w; w.x = pk_bf16(r[0], r[1]); w.y = pk_bf16(r[2], r[3]); w.z = pk_bf16(r[4], r[5]); w.w = pk_bf16(r[6], r[7]); st16_wt(rowp, w); }
;     }
.LBB0_1304:
	s_mov_b32 s101, 0
	v_mbcnt_lo_u32_b32 v0, -1, 0
	v_mbcnt_hi_u32_b32 v0, -1, v0
	s_waitcnt lgkmcnt(0)
	v_and_or_b32 v132, v0, 15, s50
	v_lshrrev_b32_e32 v0, 1, v0
	v_and_or_b32 v0, v0, 24, s51
	v_mov_b64_e32 v[2:3], s[30:31]
	s_movk_i32 s34, 0x1600
	v_lshlrev_b32_e32 v0, 1, v0
	v_mov_b32_e32 v142, 1.0
	v_mov_b32_e32 v140, 0xbfb8aa3b
	v_pk_mul_f32 v[128:129], v[124:125], v[128:129]
	v_pk_mul_f32 v[130:131], v[126:127], v[130:131]
	v_pk_mul_f32 v[120:121], v[116:117], v[120:121]
	v_pk_mul_f32 v[122:123], v[118:119], v[122:123]
	v_pk_mul_f32 v[124:125], v[124:125], v[140:141] op_sel_hi:[1,0]
	v_pk_mul_f32 v[126:127], v[126:127], v[140:141] op_sel_hi:[1,0]
	v_pk_mul_f32 v[116:117], v[116:117], v[140:141] op_sel_hi:[1,0]
	v_pk_mul_f32 v[118:119], v[118:119], v[140:141] op_sel_hi:[1,0]
	v_mad_i64_i32 v[154:155], s[4:5], v132, s34, v[2:3]
	v_lshl_add_u64 v[156:157], v[154:155], 0, v[0:1]
	v_exp_f32_e32 v124, v124
	v_exp_f32_e32 v125, v125
	v_exp_f32_e32 v126, v126
	v_exp_f32_e32 v127, v127
	v_exp_f32_e32 v116, v116
	v_exp_f32_e32 v117, v117
	v_exp_f32_e32 v118, v118
	v_exp_f32_e32 v119, v119
	v_pk_add_f32 v[124:125], v[124:125], v[142:143] op_sel_hi:[1,0]
	v_pk_add_f32 v[126:127], v[126:127], v[142:143] op_sel_hi:[1,0]
	v_pk_add_f32 v[116:117], v[116:117], v[142:143] op_sel_hi:[1,0]
	v_pk_add_f32 v[118:119], v[118:119], v[142:143] op_sel_hi:[1,0]
	v_rcp_f32_e32 v124, v124
	v_rcp_f32_e32 v125, v125
	v_rcp_f32_e32 v126, v126
	v_rcp_f32_e32 v127, v127
	v_rcp_f32_e32 v116, v116
	v_rcp_f32_e32 v117, v117
	v_rcp_f32_e32 v118, v118
	v_rcp_f32_e32 v119, v119
	v_pk_mul_f32 v[124:125], v[128:129], v[124:125]
	v_pk_mul_f32 v[126:127], v[130:131], v[126:127]
	v_pk_mul_f32 v[116:117], v[120:121], v[116:117]
	v_pk_mul_f32 v[118:119], v[122:123], v[118:119]
	v_cvt_pk_bf16_f32 v144, v124, v125
	v_cvt_pk_bf16_f32 v145, v126, v127
	v_cvt_pk_bf16_f32 v146, v116, v117
	v_cvt_pk_bf16_f32 v147, v118, v119
	global_store_dwordx4 v[156:157], v[144:147], off
	v_pk_mul_f32 v[112:113], v[108:109], v[112:113]
	v_pk_mul_f32 v[114:115], v[110:111], v[114:115]
	v_pk_mul_f32 v[104:105], v[100:101], v[104:105]
	v_pk_mul_f32 v[106:107], v[102:103], v[106:107]
	v_pk_mul_f32 v[108:109], v[108:109], v[140:141] op_sel_hi:[1,0]
	v_pk_mul_f32 v[110:111], v[110:111], v[140:141] op_sel_hi:[1,0]
	v_pk_mul_f32 v[100:101], v[100:101], v[140:141] op_sel_hi:[1,0]
	v_pk_mul_f32 v[102:103], v[102:103], v[140:141] op_sel_hi:[1,0]
	v_or_b32_e32 v152, 16, v132
	v_mad_i64_i32 v[154:155], s[4:5], v152, s34, v[2:3]
	v_lshl_add_u64 v[156:157], v[154:155], 0, v[0:1]
	v_exp_f32_e32 v108, v108
	v_exp_f32_e32 v109, v109
	v_exp_f32_e32 v110, v110
	v_exp_f32_e32 v111, v111
	v_exp_f32_e32 v100, v100
	v_exp_f32_e32 v101, v101
	v_exp_f32_e32 v102, v102
	v_exp_f32_e32 v103, v103
	v_pk_add_f32 v[108:109], v[108:109], v[142:143] op_sel_hi:[1,0]
	v_pk_add_f32 v[110:111], v[110:111], v[142:143] op_sel_hi:[1,0]
	v_pk_add_f32 v[100:101], v[100:101], v[142:143] op_sel_hi:[1,0]
	v_pk_add_f32 v[102:103], v[102:103], v[142:143] op_sel_hi:[1,0]
	v_rcp_f32_e32 v108, v108
	v_rcp_f32_e32 v109, v109
	v_rcp_f32_e32 v110, v110
	v_rcp_f32_e32 v111, v111
	v_rcp_f32_e32 v100, v100
	v_rcp_f32_e32 v101, v101
	v_rcp_f32_e32 v102, v102
	v_rcp_f32_e32 v103, v103
	v_pk_mul_f32 v[108:109], v[112:113], v[108:109]
	v_pk_mul_f32 v[110:111], v[114:115], v[110:111]
	v_pk_mul_f32 v[100:101], v[104:105], v[100:101]
	v_pk_mul_f32 v[102:103], v[106:107], v[102:103]
	v_cvt_pk_bf16_f32 v148, v108, v109
	v_cvt_pk_bf16_f32 v149, v110, v111
	v_cvt_pk_bf16_f32 v150, v100, v101
	v_cvt_pk_bf16_f32 v151, v102, v103
	global_store_dwordx4 v[156:157], v[148:151], off
	v_pk_mul_f32 v[96:97], v[92:93], v[96:97]
	v_pk_mul_f32 v[98:99], v[94:95], v[98:99]
	v_pk_mul_f32 v[88:89], v[84:85], v[88:89]
	v_pk_mul_f32 v[90:91], v[86:87], v[90:91]
	v_pk_mul_f32 v[92:93], v[92:93], v[140:141] op_sel_hi:[1,0]
	v_pk_mul_f32 v[94:95], v[94:95], v[140:141] op_sel_hi:[1,0]
	v_pk_mul_f32 v[84:85], v[84:85], v[140:141] op_sel_hi:[1,0]
	v_pk_mul_f32 v[86:87], v[86:87], v[140:141] op_sel_hi:[1,0]
	v_or_b32_e32 v152, 32, v132
	v_mad_i64_i32 v[154:155], s[4:5], v152, s34, v[2:3]
	v_lshl_add_u64 v[156:157], v[154:155], 0, v[0:1]
	v_exp_f32_e32 v92, v92
	v_exp_f32_e32 v93, v93
	v_exp_f32_e32 v94, v94
	v_exp_f32_e32 v95, v95
	v_exp_f32_e32 v84, v84
	v_exp_f32_e32 v85, v85
	v_exp_f32_e32 v86, v86
	v_exp_f32_e32 v87, v87
	v_pk_add_f32 v[92:93], v[92:93], v[142:143] op_sel_hi:[1,0]
	v_pk_add_f32 v[94:95], v[94:95], v[142:143] op_sel_hi:[1,0]
	v_pk_add_f32 v[84:85], v[84:85], v[142:143] op_sel_hi:[1,0]
	v_pk_add_f32 v[86:87], v[86:87], v[142:143] op_sel_hi:[1,0]
	v_rcp_f32_e32 v92, v92
	v_rcp_f32_e32 v93, v93
	v_rcp_f32_e32 v94, v94
	v_rcp_f32_e32 v95, v95
	v_rcp_f32_e32 v84, v84
	v_rcp_f32_e32 v85, v85
	v_rcp_f32_e32 v86, v86
	v_rcp_f32_e32 v87, v87
	v_pk_mul_f32 v[92:93], v[96:97], v[92:93]
	v_pk_mul_f32 v[94:95], v[98:99], v[94:95]
	v_pk_mul_f32 v[84:85], v[88:89], v[84:85]
	v_pk_mul_f32 v[86:87], v[90:91], v[86:87]
	v_cvt_pk_bf16_f32 v144, v92, v93
	v_cvt_pk_bf16_f32 v145, v94, v95
	v_cvt_pk_bf16_f32 v146, v84, v85
	v_cvt_pk_bf16_f32 v147, v86, v87
	global_store_dwordx4 v[156:157], v[144:147], off
	v_pk_mul_f32 v[80:81], v[76:77], v[80:81]
	v_pk_mul_f32 v[82:83], v[78:79], v[82:83]
	v_pk_mul_f32 v[68:69], v[72:73], v[68:69]
	v_pk_mul_f32 v[70:71], v[74:75], v[70:71]
	v_pk_mul_f32 v[76:77], v[76:77], v[140:141] op_sel_hi:[1,0]
	v_pk_mul_f32 v[78:79], v[78:79], v[140:141] op_sel_hi:[1,0]
	v_pk_mul_f32 v[72:73], v[72:73], v[140:141] op_sel_hi:[1,0]
	v_pk_mul_f32 v[74:75], v[74:75], v[140:141] op_sel_hi:[1,0]
	v_or_b32_e32 v152, 48, v132
	v_mad_i64_i32 v[154:155], s[4:5], v152, s34, v[2:3]
	v_lshl_add_u64 v[156:157], v[154:155], 0, v[0:1]
	v_exp_f32_e32 v76, v76
	v_exp_f32_e32 v77, v77
	v_exp_f32_e32 v78, v78
	v_exp_f32_e32 v79, v79
	v_exp_f32_e32 v72, v72
	v_exp_f32_e32 v73, v73
	v_exp_f32_e32 v74, v74
	v_exp_f32_e32 v75, v75
	v_pk_add_f32 v[76:77], v[76:77], v[142:143] op_sel_hi:[1,0]
	v_pk_add_f32 v[78:79], v[78:79], v[142:143] op_sel_hi:[1,0]
	v_pk_add_f32 v[72:73], v[72:73], v[142:143] op_sel_hi:[1,0]
	v_pk_add_f32 v[74:75], v[74:75], v[142:143] op_sel_hi:[1,0]
	v_rcp_f32_e32 v76, v76
	v_rcp_f32_e32 v77, v77
	v_rcp_f32_e32 v78, v78
	v_rcp_f32_e32 v79, v79
	v_rcp_f32_e32 v72, v72
	v_rcp_f32_e32 v73, v73
	v_rcp_f32_e32 v74, v74
	v_rcp_f32_e32 v75, v75
	v_pk_mul_f32 v[76:77], v[80:81], v[76:77]
	v_pk_mul_f32 v[78:79], v[82:83], v[78:79]
	v_pk_mul_f32 v[72:73], v[68:69], v[72:73]
	v_pk_mul_f32 v[74:75], v[70:71], v[74:75]
	v_cvt_pk_bf16_f32 v148, v76, v77
	v_cvt_pk_bf16_f32 v149, v78, v79
	v_cvt_pk_bf16_f32 v150, v72, v73
	v_cvt_pk_bf16_f32 v151, v74, v75
	global_store_dwordx4 v[156:157], v[148:151], off
	s_and_b64 vcc, exec, s[14:15]
	s_cbranch_vccz .LBB0_1329

; __device__ __forceinline__ unsigned pk_bf16(float lo, float hi) { unsigned r; asm volatile("v_cvt_pk_bf16_f32 %0, %1, %2" : "=v"(r) : "v"(lo), "v"(hi)); return r; }
;     __device__ __forceinline__ void operator()(const f32x4 (&acc)[2][2][4][2], const Unit& u, int wr, int wc, int fr, int fq) const {
;     ...
;             for (int m = 0; m < 4; ++m) { bf16_t* rowp = (bf16_t*)u.o + (size_t)(row0 + ai * HALF + m * 16) * u.ldo + col0; float r[8];
; #pragma unroll
;                 for (int bj = 0; bj < 2; ++bj) { const f32x4 a = acc[ai][bj][m][0], b = acc[ai][bj][m][1];
; #pragma unroll
;                     for (int e = 0; e < 4; ++e) r[bj * 4 + e] = a[e] * b[e] * __builtin_amdgcn_rcpf(1.f + __expf(-a[e])); }
;                 u32x4 w; w.x = pk_bf16(r[0], r[1]); w.y = pk_bf16(r[2], r[3]); w.z = pk_bf16(r[4], r[5]); w.w = pk_bf16(r[6], r[7]); st16_wt(rowp, w); }
.LBB0_1329:
	s_mov_b32 s101, 1
	v_mov_b64_e32 v[2:3], s[30:31]
	s_movk_i32 s14, 0x1600
	v_mov_b32_e32 v142, 1.0
	v_mov_b32_e32 v140, 0xbfb8aa3b
	v_pk_mul_f32 v[64:65], v[60:61], v[64:65]
	v_pk_mul_f32 v[66:67], v[62:63], v[66:67]
	v_pk_mul_f32 v[56:57], v[52:53], v[56:57]
	v_pk_mul_f32 v[58:59], v[54:55], v[58:59]
	v_pk_mul_f32 v[60:61], v[60:61], v[140:141] op_sel_hi:[1,0]
	v_pk_mul_f32 v[62:63], v[62:63], v[140:141] op_sel_hi:[1,0]
	v_pk_mul_f32 v[52:53], v[52:53], v[140:141] op_sel_hi:[1,0]
	v_pk_mul_f32 v[54:55], v[54:55], v[140:141] op_sel_hi:[1,0]
	v_add_u32_e32 v152, 0x80, v132
	v_mad_i64_i32 v[154:155], s[4:5], v152, s14, v[2:3]
	v_lshl_add_u64 v[156:157], v[154:155], 0, v[0:1]
	v_exp_f32_e32 v60, v60
	v_exp_f32_e32 v61, v61
	v_exp_f32_e32 v62, v62
	v_exp_f32_e32 v63, v63
	v_exp_f32_e32 v52, v52
	v_exp_f32_e32 v53, v53
	v_exp_f32_e32 v54, v54
	v_exp_f32_e32 v55, v55
	v_pk_add_f32 v[60:61], v[60:61], v[142:143] op_sel_hi:[1,0]
	v_pk_add_f32 v[62:63], v[62:63], v[142:143] op_sel_hi:[1,0]
	v_pk_add_f32 v[52:53], v[52:53], v[142:143] op_sel_hi:[1,0]
	v_pk_add_f32 v[54:55], v[54:55], v[142:143] op_sel_hi:[1,0]
	v_rcp_f32_e32 v60, v60
	v_rcp_f32_e32 v61, v61
	v_rcp_f32_e32 v62, v62
	v_rcp_f32_e32 v63, v63
	v_rcp_f32_e32 v52, v52
	v_rcp_f32_e32 v53, v53
	v_rcp_f32_e32 v54, v54
	v_rcp_f32_e32 v55, v55
	v_pk_mul_f32 v[60:61], v[64:65], v[60:61]
	v_pk_mul_f32 v[62:63], v[66:67], v[62:63]
	v_pk_mul_f32 v[52:53], v[56:57], v[52:53]
	v_pk_mul_f32 v[54:55], v[58:59], v[54:55]
	v_cvt_pk_bf16_f32 v144, v60, v61
	v_cvt_pk_bf16_f32 v145, v62, v63
	v_cvt_pk_bf16_f32 v146, v52, v53
	v_cvt_pk_bf16_f32 v147, v54, v55
	global_store_dwordx4 v[156:157], v[144:147], off
	v_pk_mul_f32 v[48:49], v[44:45], v[48:49]
	v_pk_mul_f32 v[50:51], v[46:47], v[50:51]
	v_pk_mul_f32 v[40:41], v[36:37], v[40:41]
	v_pk_mul_f32 v[42:43], v[38:39], v[42:43]
	v_pk_mul_f32 v[44:45], v[44:45], v[140:141] op_sel_hi:[1,0]
	v_pk_mul_f32 v[46:47], v[46:47], v[140:141] op_sel_hi:[1,0]
	v_pk_mul_f32 v[36:37], v[36:37], v[140:141] op_sel_hi:[1,0]
	v_pk_mul_f32 v[38:39], v[38:39], v[140:141] op_sel_hi:[1,0]
	v_add_u32_e32 v152, 0x90, v132
	v_mad_i64_i32 v[154:155], s[4:5], v152, s14, v[2:3]
	v_lshl_add_u64 v[156:157], v[154:155], 0, v[0:1]
	v_exp_f32_e32 v44, v44
	v_exp_f32_e32 v45, v45
	v_exp_f32_e32 v46, v46
	v_exp_f32_e32 v47, v47
	v_exp_f32_e32 v36, v36
	v_exp_f32_e32 v37, v37
	v_exp_f32_e32 v38, v38
	v_exp_f32_e32 v39, v39
	v_pk_add_f32 v[44:45], v[44:45], v[142:143] op_sel_hi:[1,0]
	v_pk_add_f32 v[46:47], v[46:47], v[142:143] op_sel_hi:[1,0]
	v_pk_add_f32 v[36:37], v[36:37], v[142:143] op_sel_hi:[1,0]
	v_pk_add_f32 v[38:39], v[38:39], v[142:143] op_sel_hi:[1,0]
	v_rcp_f32_e32 v44, v44
	v_rcp_f32_e32 v45, v45
	v_rcp_f32_e32 v46, v46
	v_rcp_f32_e32 v47, v47
	v_rcp_f32_e32 v36, v36
	v_rcp_f32_e32 v37, v37
	v_rcp_f32_e32 v38, v38
	v_rcp_f32_e32 v39, v39
	v_pk_mul_f32 v[44:45], v[48:49], v[44:45]
	v_pk_mul_f32 v[46:47], v[50:51], v[46:47]
	v_pk_mul_f32 v[36:37], v[40:41], v[36:37]
	v_pk_mul_f32 v[38:39], v[42:43], v[38:39]
	v_cvt_pk_bf16_f32 v148, v44, v45
	v_cvt_pk_bf16_f32 v149, v46, v47
	v_cvt_pk_bf16_f32 v150, v36, v37
	v_cvt_pk_bf16_f32 v151, v38, v39
	global_store_dwordx4 v[156:157], v[148:151], off
	v_pk_mul_f32 v[32:33], v[28:29], v[32:33]
	v_pk_mul_f32 v[34:35], v[30:31], v[34:35]
	v_pk_mul_f32 v[24:25], v[20:21], v[24:25]
	v_pk_mul_f32 v[26:27], v[22:23], v[26:27]
	v_pk_mul_f32 v[28:29], v[28:29], v[140:141] op_sel_hi:[1,0]
	v_pk_mul_f32 v[30:31], v[30:31], v[140:141] op_sel_hi:[1,0]
	v_pk_mul_f32 v[20:21], v[20:21], v[140:141] op_sel_hi:[1,0]
	v_pk_mul_f32 v[22:23], v[22:23], v[140:141] op_sel_hi:[1,0]
	v_add_u32_e32 v152, 0xa0, v132
	v_mad_i64_i32 v[154:155], s[4:5], v152, s14, v[2:3]
	v_lshl_add_u64 v[156:157], v[154:155], 0, v[0:1]
	v_exp_f32_e32 v28, v28
	v_exp_f32_e32 v29, v29
	v_exp_f32_e32 v30, v30
	v_exp_f32_e32 v31, v31
	v_exp_f32_e32 v20, v20
	v_exp_f32_e32 v21, v21
	v_exp_f32_e32 v22, v22
	v_exp_f32_e32 v23, v23
	v_pk_add_f32 v[28:29], v[28:29], v[142:143] op_sel_hi:[1,0]
	v_pk_add_f32 v[30:31], v[30:31], v[142:143] op_sel_hi:[1,0]
	v_pk_add_f32 v[20:21], v[20:21], v[142:143] op_sel_hi:[1,0]
	v_pk_add_f32 v[22:23], v[22:23], v[142:143] op_sel_hi:[1,0]
	v_rcp_f32_e32 v28, v28
	v_rcp_f32_e32 v29, v29
	v_rcp_f32_e32 v30, v30
	v_rcp_f32_e32 v31, v31
	v_rcp_f32_e32 v20, v20
	v_rcp_f32_e32 v21, v21
	v_rcp_f32_e32 v22, v22
	v_rcp_f32_e32 v23, v23
	v_pk_mul_f32 v[28:29], v[32:33], v[28:29]
	v_pk_mul_f32 v[30:31], v[34:35], v[30:31]
	v_pk_mul_f32 v[20:21], v[24:25], v[20:21]
	v_pk_mul_f32 v[22:23], v[26:27], v[22:23]
	v_cvt_pk_bf16_f32 v144, v28, v29
	v_cvt_pk_bf16_f32 v145, v30, v31
	v_cvt_pk_bf16_f32 v146, v20, v21
	v_cvt_pk_bf16_f32 v147, v22, v23
	global_store_dwordx4 v[156:157], v[144:147], off
	v_pk_mul_f32 v[16:17], v[12:13], v[16:17]
	v_pk_mul_f32 v[18:19], v[14:15], v[18:19]
	v_pk_mul_f32 v[8:9], v[4:5], v[8:9]
	v_pk_mul_f32 v[10:11], v[6:7], v[10:11]
	v_pk_mul_f32 v[12:13], v[12:13], v[140:141] op_sel_hi:[1,0]
	v_pk_mul_f32 v[14:15], v[14:15], v[140:141] op_sel_hi:[1,0]
	v_pk_mul_f32 v[4:5], v[4:5], v[140:141] op_sel_hi:[1,0]
	v_pk_mul_f32 v[6:7], v[6:7], v[140:141] op_sel_hi:[1,0]
	v_add_u32_e32 v152, 0xb0, v132
	v_mad_i64_i32 v[154:155], s[4:5], v152, s14, v[2:3]
	v_lshl_add_u64 v[156:157], v[154:155], 0, v[0:1]
	v_exp_f32_e32 v12, v12
	v_exp_f32_e32 v13, v13
	v_exp_f32_e32 v14, v14
	v_exp_f32_e32 v15, v15
	v_exp_f32_e32 v4, v4
	v_exp_f32_e32 v5, v5
	v_exp_f32_e32 v6, v6
	v_exp_f32_e32 v7, v7
	v_pk_add_f32 v[12:13], v[12:13], v[142:143] op_sel_hi:[1,0]
	v_pk_add_f32 v[14:15], v[14:15], v[142:143] op_sel_hi:[1,0]
	v_pk_add_f32 v[4:5], v[4:5], v[142:143] op_sel_hi:[1,0]
	v_pk_add_f32 v[6:7], v[6:7], v[142:143] op_sel_hi:[1,0]
	v_rcp_f32_e32 v12, v12
	v_rcp_f32_e32 v13, v13
	v_rcp_f32_e32 v14, v14
	v_rcp_f32_e32 v15, v15
	v_rcp_f32_e32 v4, v4
	v_rcp_f32_e32 v5, v5
	v_rcp_f32_e32 v6, v6
	v_rcp_f32_e32 v7, v7
	v_pk_mul_f32 v[12:13], v[16:17], v[12:13]
	v_pk_mul_f32 v[14:15], v[18:19], v[14:15]
	v_pk_mul_f32 v[4:5], v[8:9], v[4:5]
	v_pk_mul_f32 v[6:7], v[10:11], v[6:7]
	v_cvt_pk_bf16_f32 v148, v12, v13
	v_cvt_pk_bf16_f32 v149, v14, v15
	v_cvt_pk_bf16_f32 v150, v4, v5
	v_cvt_pk_bf16_f32 v151, v6, v7
	global_store_dwordx4 v[156:157], v[148:151], off
	s_branch .LBB0_1305
